# NSA selected-pass row-max tree via v_max3 (drop redundant canonicalize), no gratuitous lgkm waits; wconv ticket prefetch removed
# speedup vs baseline: 1.0049x; 1.0049x over previous
; DI float shx_(float v, int m) { return __int_as_float(__builtin_amdgcn_ds_bpermute((lane_pinned_() ^ m) << 2, __float_as_int(v))); }
; DI int shx_(int v, int m) { return __builtin_amdgcn_ds_bpermute((lane_pinned_() ^ m) << 2, v); }
; template <int MODE> ...
;     ...
;         float mr = fmaxf(fmaxf(acc[0], acc[1]), fmaxf(acc[2], acc[3]));
; #pragma unroll
;         for (int i = 4; i < 16; i += 2) mr = fmaxf(mr, fmaxf(acc[i], acc[i + 1]));
;         float mx = fmaxf(m, mr * C);
;         if (MODE == 2) mx = bit ? mx : m;
;         mx = fmaxf(mx, shx_(mx, 32));
;         if (MODE >= 2) mx = (mx > m + 8.f) ? mx : m;
;         if (MODE == 0) { l *= __builtin_amdgcn_exp2f(m - mx); }
.LBB0_166:
	s_or_b64 exec, exec, s[2:3]
	ds_read2_b64 v[242:245], v188 offset1:2
	ds_read2_b64 v[246:249], v188 offset0:4 offset1:6
	s_nop 8
	v_max3_f32 v200, v66, v67, v68
	v_max3_f32 v202, v69, v70, v71
	v_max3_f32 v203, v72, v73, v74
	v_max3_f32 v214, v75, v76, v77
	v_max3_f32 v200, v200, v78, v79
	v_max3_f32 v202, v202, v80, v81
	v_max3_f32 v200, v200, v202, v203
	v_max_f32_e32 v200, v200, v214
	v_mul_f32_e32 v200, 0x3e0293ee, v200
	v_max_f32_e32 v202, v166, v166
	v_max_f32_e32 v200, v202, v200
	v_cndmask_b32_e64 v200, v166, v200, s[0:1]
	v_mov_b32_e32 v202, v200
	s_nop 1
	v_permlane32_swap_b32 v202, v200
	s_nop 0
	v_max_f32_e32 v200, v200, v202
	v_add_f32_e32 v202, 0x41000000, v166
	v_cmp_gt_f32_e32 vcc, v200, v202
	s_nop 1
	v_cndmask_b32_e32 v200, v166, v200, vcc
	v_cmp_gt_f32_e32 vcc, v200, v166
	s_cbranch_vccz .LBB0_168
	v_sub_f32_e32 v166, v166, v200
	v_exp_f32_e32 v166, v166
	s_nop 0
	v_mul_f32_e32 v167, v167, v166
	v_pk_mul_f32 v[64:65], v[64:65], v[166:167] op_sel_hi:[1,0]
	v_pk_mul_f32 v[62:63], v[62:63], v[166:167] op_sel_hi:[1,0]
	v_pk_mul_f32 v[60:61], v[60:61], v[166:167] op_sel_hi:[1,0]
	v_pk_mul_f32 v[58:59], v[58:59], v[166:167] op_sel_hi:[1,0]
	v_pk_mul_f32 v[56:57], v[56:57], v[166:167] op_sel_hi:[1,0]
	v_pk_mul_f32 v[54:55], v[54:55], v[166:167] op_sel_hi:[1,0]
	v_pk_mul_f32 v[52:53], v[52:53], v[166:167] op_sel_hi:[1,0]
	v_pk_mul_f32 v[50:51], v[50:51], v[166:167] op_sel_hi:[1,0]
	v_pk_mul_f32 v[48:49], v[48:49], v[166:167] op_sel_hi:[1,0]
	v_pk_mul_f32 v[46:47], v[46:47], v[166:167] op_sel_hi:[1,0]
	v_pk_mul_f32 v[44:45], v[44:45], v[166:167] op_sel_hi:[1,0]
	v_pk_mul_f32 v[42:43], v[42:43], v[166:167] op_sel_hi:[1,0]
	v_pk_mul_f32 v[40:41], v[40:41], v[166:167] op_sel_hi:[1,0]
	v_pk_mul_f32 v[38:39], v[38:39], v[166:167] op_sel_hi:[1,0]
	v_pk_mul_f32 v[36:37], v[36:37], v[166:167] op_sel_hi:[1,0]
	v_pk_mul_f32 v[34:35], v[34:35], v[166:167] op_sel_hi:[1,0]
	v_pk_mul_f32 v[32:33], v[32:33], v[166:167] op_sel_hi:[1,0]
	v_pk_mul_f32 v[30:31], v[30:31], v[166:167] op_sel_hi:[1,0]
	v_pk_mul_f32 v[28:29], v[28:29], v[166:167] op_sel_hi:[1,0]
	v_pk_mul_f32 v[26:27], v[26:27], v[166:167] op_sel_hi:[1,0]
	v_pk_mul_f32 v[24:25], v[24:25], v[166:167] op_sel_hi:[1,0]
	v_pk_mul_f32 v[22:23], v[22:23], v[166:167] op_sel_hi:[1,0]
	v_pk_mul_f32 v[20:21], v[20:21], v[166:167] op_sel_hi:[1,0]
	v_pk_mul_f32 v[18:19], v[18:19], v[166:167] op_sel_hi:[1,0]
	v_pk_mul_f32 v[16:17], v[16:17], v[166:167] op_sel_hi:[1,0]
	v_pk_mul_f32 v[14:15], v[14:15], v[166:167] op_sel_hi:[1,0]
	v_pk_mul_f32 v[12:13], v[12:13], v[166:167] op_sel_hi:[1,0]
	v_pk_mul_f32 v[10:11], v[10:11], v[166:167] op_sel_hi:[1,0]
	v_pk_mul_f32 v[8:9], v[8:9], v[166:167] op_sel_hi:[1,0]
	v_pk_mul_f32 v[6:7], v[6:7], v[166:167] op_sel_hi:[1,0]
	v_pk_mul_f32 v[4:5], v[4:5], v[166:167] op_sel_hi:[1,0]
	v_pk_mul_f32 v[2:3], v[2:3], v[166:167] op_sel_hi:[1,0]
.LBB0_168:
	v_cmp_ngt_f32_e32 vcc, s45, v200
	s_and_b64 s[0:1], s[0:1], vcc
	v_cndmask_b32_e64 v166, v209, -v200, s[0:1]
	v_fmamk_f32 v66, v66, 0x3e0293ee, v166
	v_exp_f32_e32 v66, v66
	v_fmamk_f32 v67, v67, 0x3e0293ee, v166
	v_exp_f32_e32 v67, v67
	v_fmamk_f32 v68, v68, 0x3e0293ee, v166
	v_exp_f32_e32 v68, v68
	v_fmamk_f32 v69, v69, 0x3e0293ee, v166
	v_exp_f32_e32 v69, v69
	v_fmamk_f32 v70, v70, 0x3e0293ee, v166
	v_add_f32_e32 v202, 0, v66
	v_exp_f32_e32 v203, v70
	v_add_f32_e32 v202, v67, v202
	v_add_f32_e32 v202, v68, v202
	v_add_f32_e32 v202, v69, v202
	v_fmamk_f32 v71, v71, 0x3e0293ee, v166
	v_add_f32_e32 v70, v203, v202
	v_exp_f32_e32 v202, v71
	v_fmamk_f32 v71, v72, 0x3e0293ee, v166
	v_exp_f32_e32 v214, v71
	v_fmamk_f32 v71, v73, 0x3e0293ee, v166
	v_exp_f32_e32 v73, v71
	v_fmamk_f32 v71, v74, 0x3e0293ee, v166
	v_exp_f32_e32 v74, v71
	v_fmamk_f32 v71, v75, 0x3e0293ee, v166
	v_add_f32_e32 v70, v202, v70
	v_exp_f32_e32 v75, v71
	v_fmamk_f32 v71, v76, 0x3e0293ee, v166
	v_add_f32_e32 v70, v214, v70
	v_exp_f32_e32 v76, v71
	v_fmamk_f32 v71, v77, 0x3e0293ee, v166
	v_add_f32_e32 v70, v73, v70
	v_exp_f32_e32 v77, v71
	v_fmamk_f32 v71, v78, 0x3e0293ee, v166
	v_add_f32_e32 v70, v74, v70
	v_exp_f32_e32 v78, v71
	v_fmamk_f32 v71, v79, 0x3e0293ee, v166
	v_add_f32_e32 v70, v75, v70
	v_exp_f32_e32 v79, v71
	v_fmamk_f32 v71, v80, 0x3e0293ee, v166
	v_add_f32_e32 v70, v76, v70
	v_exp_f32_e32 v80, v71
	v_fmac_f32_e32 v166, 0x3e0293ee, v81
	v_add_f32_e32 v70, v77, v70
	v_exp_f32_e32 v81, v166
	v_add_f32_e32 v70, v78, v70
	v_add_f32_e32 v70, v79, v70
	v_add_f32_e32 v70, v80, v70
	v_add_f32_e32 v70, v81, v70
	v_mov_b32_e32 v71, v70
	s_nop 1
	v_permlane32_swap_b32 v71, v70
	s_nop 0
	v_cvt_pk_bf16_f32 v72, v203, v202
	v_cvt_pk_bf16_f32 v73, v214, v73
	v_add_f32_e32 v70, v70, v71
	v_add_f32_e32 v167, v167, v70
	v_cvt_pk_bf16_f32 v70, v66, v67
	v_cvt_pk_bf16_f32 v71, v68, v69
	v_cvt_pk_bf16_f32 v66, v74, v75
	v_cvt_pk_bf16_f32 v67, v76, v77
	v_cvt_pk_bf16_f32 v68, v78, v79
	v_cvt_pk_bf16_f32 v69, v80, v81
	ds_read2_b64 v[74:77], v193 offset0:64 offset1:66
	ds_read2_b64 v[78:81], v193 offset0:68 offset1:70
	s_waitcnt lgkmcnt(3)
	v_mfma_f32_32x32x16_bf16 v[50:65], v[242:245], v[70:73], v[50:65]
	s_waitcnt lgkmcnt(2)
	v_mfma_f32_32x32x16_bf16 v[50:65], v[246:249], v[66:69], v[50:65]
	ds_read2_b64 v[242:245], v194 offset0:128 offset1:130
	ds_read2_b64 v[246:249], v194 offset0:132 offset1:134
	s_waitcnt lgkmcnt(3)
	v_mfma_f32_32x32x16_bf16 v[34:49], v[74:77], v[70:73], v[34:49]
	s_waitcnt lgkmcnt(2)
	v_mfma_f32_32x32x16_bf16 v[34:49], v[78:81], v[66:69], v[34:49]
	ds_read2_b64 v[74:77], v195 offset0:192 offset1:194
	ds_read2_b64 v[78:81], v195 offset0:196 offset1:198
	s_waitcnt lgkmcnt(3)
	v_mfma_f32_32x32x16_bf16 v[18:33], v[242:245], v[70:73], v[18:33]
	s_waitcnt lgkmcnt(2)
	v_mfma_f32_32x32x16_bf16 v[18:33], v[246:249], v[66:69], v[18:33]
	s_waitcnt lgkmcnt(1)
	v_mfma_f32_32x32x16_bf16 v[2:17], v[74:77], v[70:73], v[2:17]
	s_waitcnt lgkmcnt(0)
	v_mfma_f32_32x32x16_bf16 v[2:17], v[78:81], v[66:69], v[2:17]
	s_cmp_lt_u32 s11, s12
	s_cselect_b64 s[0:1], -1, 0
	s_cmp_ge_u32 s11, s12
	s_cbranch_scc1 .LBB0_170

; DI float shx_(float v, int m) { return __int_as_float(__builtin_amdgcn_ds_bpermute((lane_pinned_() ^ m) << 2, __float_as_int(v))); }
; DI int shx_(int v, int m) { return __builtin_amdgcn_ds_bpermute((lane_pinned_() ^ m) << 2, v); }
; template <int MODE> ...
;     ...
;         float mr = fmaxf(fmaxf(acc[0], acc[1]), fmaxf(acc[2], acc[3]));
; #pragma unroll
;         for (int i = 4; i < 16; i += 2) mr = fmaxf(mr, fmaxf(acc[i], acc[i + 1]));
;         float mx = fmaxf(m, mr * C);
;         if (MODE == 2) mx = bit ? mx : m;
;         mx = fmaxf(mx, shx_(mx, 32));
;         if (MODE >= 2) mx = (mx > m + 8.f) ? mx : m;
;         if (MODE == 0) { l *= __builtin_amdgcn_exp2f(m - mx); }
.LBB0_176:
	s_or_b64 exec, exec, s[2:3]
	v_add_u32_e32 v215, v187, v186
	v_add_u32_e32 v216, 0x2000, v215
	v_add_u32_e32 v217, 0x3000, v215
	ds_read2_b64 v[242:245], v215 offset1:2
	ds_read2_b64 v[246:249], v215 offset0:4 offset1:6
	s_nop 8
	v_max3_f32 v166, v66, v67, v68
	v_max3_f32 v201, v69, v70, v71
	v_max3_f32 v202, v72, v73, v74
	v_max3_f32 v203, v75, v76, v77
	v_max3_f32 v166, v166, v78, v79
	v_max3_f32 v201, v201, v80, v81
	v_max3_f32 v166, v166, v201, v202
	v_max_f32_e32 v166, v166, v203
	v_mul_f32_e32 v166, 0x3e0293ee, v166
	v_max_f32_e32 v201, v200, v200
	v_max_f32_e32 v166, v201, v166
	v_cndmask_b32_e64 v166, v200, v166, s[0:1]
	v_mov_b32_e32 v201, v166
	s_nop 1
	v_permlane32_swap_b32 v201, v166
	s_nop 0
	v_max_f32_e32 v166, v166, v201
	v_add_f32_e32 v201, 0x41000000, v200
	v_cmp_gt_f32_e32 vcc, v166, v201
	s_nop 1
	v_cndmask_b32_e32 v166, v200, v166, vcc
	v_cmp_gt_f32_e32 vcc, v166, v200
	s_cbranch_vccz .LBB0_178
	v_sub_f32_e32 v200, v200, v166
	v_exp_f32_e32 v200, v200
	s_nop 0
	v_mul_f32_e32 v167, v167, v200
	v_pk_mul_f32 v[64:65], v[64:65], v[200:201] op_sel_hi:[1,0]
	v_pk_mul_f32 v[62:63], v[62:63], v[200:201] op_sel_hi:[1,0]
	v_pk_mul_f32 v[60:61], v[60:61], v[200:201] op_sel_hi:[1,0]
	v_pk_mul_f32 v[58:59], v[58:59], v[200:201] op_sel_hi:[1,0]
	v_pk_mul_f32 v[56:57], v[56:57], v[200:201] op_sel_hi:[1,0]
	v_pk_mul_f32 v[54:55], v[54:55], v[200:201] op_sel_hi:[1,0]
	v_pk_mul_f32 v[52:53], v[52:53], v[200:201] op_sel_hi:[1,0]
	v_pk_mul_f32 v[50:51], v[50:51], v[200:201] op_sel_hi:[1,0]
	v_pk_mul_f32 v[48:49], v[48:49], v[200:201] op_sel_hi:[1,0]
	v_pk_mul_f32 v[46:47], v[46:47], v[200:201] op_sel_hi:[1,0]
	v_pk_mul_f32 v[44:45], v[44:45], v[200:201] op_sel_hi:[1,0]
	v_pk_mul_f32 v[42:43], v[42:43], v[200:201] op_sel_hi:[1,0]
	v_pk_mul_f32 v[40:41], v[40:41], v[200:201] op_sel_hi:[1,0]
	v_pk_mul_f32 v[38:39], v[38:39], v[200:201] op_sel_hi:[1,0]
	v_pk_mul_f32 v[36:37], v[36:37], v[200:201] op_sel_hi:[1,0]
	v_pk_mul_f32 v[34:35], v[34:35], v[200:201] op_sel_hi:[1,0]
	v_pk_mul_f32 v[32:33], v[32:33], v[200:201] op_sel_hi:[1,0]
	v_pk_mul_f32 v[30:31], v[30:31], v[200:201] op_sel_hi:[1,0]
	v_pk_mul_f32 v[28:29], v[28:29], v[200:201] op_sel_hi:[1,0]
	v_pk_mul_f32 v[26:27], v[26:27], v[200:201] op_sel_hi:[1,0]
	v_pk_mul_f32 v[24:25], v[24:25], v[200:201] op_sel_hi:[1,0]
	v_pk_mul_f32 v[22:23], v[22:23], v[200:201] op_sel_hi:[1,0]
	v_pk_mul_f32 v[20:21], v[20:21], v[200:201] op_sel_hi:[1,0]
	v_pk_mul_f32 v[18:19], v[18:19], v[200:201] op_sel_hi:[1,0]
	v_pk_mul_f32 v[16:17], v[16:17], v[200:201] op_sel_hi:[1,0]
	v_pk_mul_f32 v[14:15], v[14:15], v[200:201] op_sel_hi:[1,0]
	v_pk_mul_f32 v[12:13], v[12:13], v[200:201] op_sel_hi:[1,0]
	v_pk_mul_f32 v[10:11], v[10:11], v[200:201] op_sel_hi:[1,0]
	v_pk_mul_f32 v[8:9], v[8:9], v[200:201] op_sel_hi:[1,0]
	v_pk_mul_f32 v[6:7], v[6:7], v[200:201] op_sel_hi:[1,0]
	v_pk_mul_f32 v[4:5], v[4:5], v[200:201] op_sel_hi:[1,0]
	v_pk_mul_f32 v[2:3], v[2:3], v[200:201] op_sel_hi:[1,0]
.LBB0_178:
	v_cmp_ngt_f32_e32 vcc, s45, v166
	s_and_b64 s[0:1], s[0:1], vcc
	v_cndmask_b32_e64 v200, v209, -v166, s[0:1]
	v_fmamk_f32 v66, v66, 0x3e0293ee, v200
	v_exp_f32_e32 v66, v66
	v_fmamk_f32 v67, v67, 0x3e0293ee, v200
	v_exp_f32_e32 v67, v67
	v_fmamk_f32 v68, v68, 0x3e0293ee, v200
	v_exp_f32_e32 v68, v68
	v_fmamk_f32 v69, v69, 0x3e0293ee, v200
	v_exp_f32_e32 v69, v69
	v_fmamk_f32 v70, v70, 0x3e0293ee, v200
	v_add_f32_e32 v201, 0, v66
	v_exp_f32_e32 v202, v70
	v_add_f32_e32 v201, v67, v201
	v_add_f32_e32 v201, v68, v201
	v_add_f32_e32 v201, v69, v201
	v_fmamk_f32 v71, v71, 0x3e0293ee, v200
	v_add_f32_e32 v70, v202, v201
	v_exp_f32_e32 v201, v71
	v_fmamk_f32 v71, v72, 0x3e0293ee, v200
	v_exp_f32_e32 v203, v71
	v_fmamk_f32 v71, v73, 0x3e0293ee, v200
	v_exp_f32_e32 v73, v71
	v_fmamk_f32 v71, v74, 0x3e0293ee, v200
	v_exp_f32_e32 v74, v71
	v_fmamk_f32 v71, v75, 0x3e0293ee, v200
	v_add_f32_e32 v70, v201, v70
	v_exp_f32_e32 v75, v71
	v_fmamk_f32 v71, v76, 0x3e0293ee, v200
	v_add_f32_e32 v70, v203, v70
	v_exp_f32_e32 v76, v71
	v_fmamk_f32 v71, v77, 0x3e0293ee, v200
	v_add_f32_e32 v70, v73, v70
	v_exp_f32_e32 v77, v71
	v_fmamk_f32 v71, v78, 0x3e0293ee, v200
	v_add_f32_e32 v70, v74, v70
	v_exp_f32_e32 v78, v71
	v_fmamk_f32 v71, v79, 0x3e0293ee, v200
	v_add_f32_e32 v70, v75, v70
	v_exp_f32_e32 v79, v71
	v_fmamk_f32 v71, v80, 0x3e0293ee, v200
	v_add_f32_e32 v70, v76, v70
	v_exp_f32_e32 v80, v71
	v_fmac_f32_e32 v200, 0x3e0293ee, v81
	v_add_f32_e32 v70, v77, v70
	v_exp_f32_e32 v81, v200
	v_add_f32_e32 v70, v78, v70
	v_add_f32_e32 v70, v79, v70
	v_add_f32_e32 v70, v80, v70
	v_add_f32_e32 v70, v81, v70
	v_mov_b32_e32 v71, v70
	s_nop 1
	v_permlane32_swap_b32 v71, v70
	s_nop 0
	v_cvt_pk_bf16_f32 v72, v202, v201
	v_cvt_pk_bf16_f32 v73, v203, v73
	v_add_f32_e32 v70, v70, v71
	v_add_f32_e32 v167, v167, v70
	v_cvt_pk_bf16_f32 v70, v66, v67
	v_cvt_pk_bf16_f32 v71, v68, v69
	v_cvt_pk_bf16_f32 v66, v74, v75
	v_cvt_pk_bf16_f32 v67, v76, v77
	v_cvt_pk_bf16_f32 v68, v78, v79
	v_cvt_pk_bf16_f32 v69, v80, v81
	v_add_u32_e32 v78, 0x1000, v215
	ds_read2_b64 v[74:77], v78 offset0:64 offset1:66
	ds_read2_b64 v[78:81], v78 offset0:68 offset1:70
	s_waitcnt lgkmcnt(3)
	v_mfma_f32_32x32x16_bf16 v[50:65], v[242:245], v[70:73], v[50:65]
	s_waitcnt lgkmcnt(2)
	v_mfma_f32_32x32x16_bf16 v[50:65], v[246:249], v[66:69], v[50:65]
	ds_read2_b64 v[242:245], v216 offset0:128 offset1:130
	ds_read2_b64 v[246:249], v216 offset0:132 offset1:134
	s_waitcnt lgkmcnt(3)
	v_mfma_f32_32x32x16_bf16 v[34:49], v[74:77], v[70:73], v[34:49]
	s_waitcnt lgkmcnt(2)
	v_mfma_f32_32x32x16_bf16 v[34:49], v[78:81], v[66:69], v[34:49]
	ds_read2_b64 v[74:77], v217 offset0:192 offset1:194
	ds_read2_b64 v[78:81], v217 offset0:196 offset1:198
	s_waitcnt lgkmcnt(3)
	v_mfma_f32_32x32x16_bf16 v[18:33], v[242:245], v[70:73], v[18:33]
	s_waitcnt lgkmcnt(2)
	v_mfma_f32_32x32x16_bf16 v[18:33], v[246:249], v[66:69], v[18:33]
	s_waitcnt lgkmcnt(1)
	v_mfma_f32_32x32x16_bf16 v[2:17], v[74:77], v[70:73], v[2:17]
	s_waitcnt lgkmcnt(0)
	v_mfma_f32_32x32x16_bf16 v[2:17], v[78:81], v[66:69], v[2:17]
	s_mov_b64 s[0:1], 0x8000
	s_cmp_ge_u32 s8, s12
	s_cbranch_scc1 .LBB0_180
